# G split-K slab sum for the sample rows rewritten: all 40 loads of a thread's four items in flight before the first add (was one slab per wait)
# speedup vs baseline: 1.0091x; 1.0008x over previous
; __global__ void __launch_bounds__(NWAVES * 64, 2) mk_fwd(Args args) {
;     ...
;                 xcd_barrier(bar);
;                 {
;                     const float* part = (const float*)(ws + WS_PART); const float* gate = modf_l + 2 * DM;
;                     f32x4 ra[4], rx[4], rg[4];
; #pragma unroll
;                     for (int q = 0; q < 4; ++q) { const int idx = q * (G * 512) + bx * 512 + tid, r = idx >> 10, c = (idx & 1023) * 4;
;                         const float* pp = part + ((size_t)(((r >> 8) * 16 + (c >> 8)) * 8) * 65536 + (size_t)(r & 255) * 256 + (c & 255));
;                         f32x4 a = *(const f32x4*)pp;
; #pragma unroll
;                         for (int k2 = 1; k2 < 8; ++k2) a += *(const f32x4*)(pp + (size_t)k2 * 65536);
;                         ra[q] = a; rx[q] = *(const f32x4*)(xs + (size_t)r * DM + c); rg[q] = *(const f32x4*)(gate + (size_t)(4 + (r >> 5)) * (3 * DM) + c); }
; #pragma unroll
;                     for (int q = 0; q < 4; ++q) { const int idx = q * (G * 512) + bx * 512 + tid, r = idx >> 10, c = (idx & 1023) * 4;
.LBB0_1469:
	s_or_b64 exec, exec, s[8:9]
	v_add_u32_e32 v214, s19, v206
	v_mov_b32_e32 v229, v3
	v_lshlrev_b32_e32 v216, 2, v214
	v_and_b32_e32 v228, 0xffc, v216
	v_bfe_u32 v216, v216, 8, 4
	v_ashrrev_i32_e32 v217, 14, v214
	s_mov_b32 s10, 0x1ffffff0
	v_and_or_b32 v216, v217, s10, v216
	v_lshlrev_b32_e32 v216, 3, v216
	v_ashrrev_i32_e32 v217, 31, v216
	v_lshlrev_b64 v[216:217], 18, v[216:217]
	v_lshl_add_u64 v[216:217], s[2:3], 0, v[216:217]
	v_and_b32_e32 v228, 0x3fc00, v214
	v_lshl_add_u64 v[216:217], v[216:217], 0, v[228:229]
	v_lshlrev_b32_e32 v228, 4, v214
	v_and_b32_e32 v228, 0x3f0, v228
	v_lshl_add_u64 v[218:219], v[216:217], 0, v[228:229]
	v_ashrrev_i32_e32 v216, 10, v214
	v_ashrrev_i32_e32 v217, 31, v216
	v_lshlrev_b64 v[216:217], 14, v[216:217]
	v_lshlrev_b32_e32 v228, 2, v214
	v_and_b32_e32 v228, 0xffc, v228
	v_lshlrev_b32_e32 v228, 2, v228
	v_lshl_add_u64 v[226:227], s[0:1], 0, v[216:217]
	v_lshl_add_u64 v[230:231], v[226:227], 0, v[228:229]
	v_lshl_add_u64 v[226:227], s[6:7], 0, v[216:217]
	v_lshl_add_u64 v[238:239], v[226:227], 0, v[228:229]
	v_ashrrev_i32_e32 v216, 15, v214
	v_mul_i32_i24_e32 v216, 0x3000, v216
	v_ashrrev_i32_e32 v217, 31, v216
	v_lshl_add_u64 v[216:217], v[216:217], 2, s[4:5]
	v_lshl_add_u64 v[216:217], v[216:217], 0, v[228:229]
	s_mov_b64 s[36:37], 0x30000
	v_lshl_add_u64 v[174:175], v[216:217], 0, s[36:37]
	v_add_u32_e32 v215, 0x20000, v214
	v_lshlrev_b32_e32 v216, 2, v215
	v_and_b32_e32 v228, 0xffc, v216
	v_bfe_u32 v216, v216, 8, 4
	v_ashrrev_i32_e32 v217, 14, v215
	s_mov_b32 s10, 0x1ffffff0
	v_and_or_b32 v216, v217, s10, v216
	v_lshlrev_b32_e32 v216, 3, v216
	v_ashrrev_i32_e32 v217, 31, v216
	v_lshlrev_b64 v[216:217], 18, v[216:217]
	v_lshl_add_u64 v[216:217], s[2:3], 0, v[216:217]
	v_and_b32_e32 v228, 0x3fc00, v215
	v_lshl_add_u64 v[216:217], v[216:217], 0, v[228:229]
	v_lshlrev_b32_e32 v228, 4, v215
	v_and_b32_e32 v228, 0x3f0, v228
	v_lshl_add_u64 v[220:221], v[216:217], 0, v[228:229]
	v_ashrrev_i32_e32 v216, 10, v215
	v_ashrrev_i32_e32 v217, 31, v216
	v_lshlrev_b64 v[216:217], 14, v[216:217]
	v_lshlrev_b32_e32 v228, 2, v215
	v_and_b32_e32 v228, 0xffc, v228
	v_lshlrev_b32_e32 v228, 2, v228
	v_lshl_add_u64 v[226:227], s[0:1], 0, v[216:217]
	v_lshl_add_u64 v[232:233], v[226:227], 0, v[228:229]
	v_lshl_add_u64 v[226:227], s[6:7], 0, v[216:217]
	v_lshl_add_u64 v[240:241], v[226:227], 0, v[228:229]
	v_ashrrev_i32_e32 v216, 15, v215
	v_mul_i32_i24_e32 v216, 0x3000, v216
	v_ashrrev_i32_e32 v217, 31, v216
	v_lshl_add_u64 v[216:217], v[216:217], 2, s[4:5]
	v_lshl_add_u64 v[216:217], v[216:217], 0, v[228:229]
	s_mov_b64 s[36:37], 0x30000
	v_lshl_add_u64 v[176:177], v[216:217], 0, s[36:37]
	v_add_u32_e32 v215, 0x40000, v214
	v_lshlrev_b32_e32 v216, 2, v215
	v_and_b32_e32 v228, 0xffc, v216
	v_bfe_u32 v216, v216, 8, 4
	v_ashrrev_i32_e32 v217, 14, v215
	s_mov_b32 s10, 0x1ffffff0
	v_and_or_b32 v216, v217, s10, v216
	v_lshlrev_b32_e32 v216, 3, v216
	v_ashrrev_i32_e32 v217, 31, v216
	v_lshlrev_b64 v[216:217], 18, v[216:217]
	v_lshl_add_u64 v[216:217], s[2:3], 0, v[216:217]
	v_and_b32_e32 v228, 0x3fc00, v215
	v_lshl_add_u64 v[216:217], v[216:217], 0, v[228:229]
	v_lshlrev_b32_e32 v228, 4, v215
	v_and_b32_e32 v228, 0x3f0, v228
	v_lshl_add_u64 v[222:223], v[216:217], 0, v[228:229]
	v_ashrrev_i32_e32 v216, 10, v215
	v_ashrrev_i32_e32 v217, 31, v216
	v_lshlrev_b64 v[216:217], 14, v[216:217]
	v_lshlrev_b32_e32 v228, 2, v215
	v_and_b32_e32 v228, 0xffc, v228
	v_lshlrev_b32_e32 v228, 2, v228
	v_lshl_add_u64 v[226:227], s[0:1], 0, v[216:217]
	v_lshl_add_u64 v[234:235], v[226:227], 0, v[228:229]
	v_lshl_add_u64 v[226:227], s[6:7], 0, v[216:217]
	v_lshl_add_u64 v[242:243], v[226:227], 0, v[228:229]
	v_ashrrev_i32_e32 v216, 15, v215
	v_mul_i32_i24_e32 v216, 0x3000, v216
	v_ashrrev_i32_e32 v217, 31, v216
	v_lshl_add_u64 v[216:217], v[216:217], 2, s[4:5]
	v_lshl_add_u64 v[216:217], v[216:217], 0, v[228:229]
	s_mov_b64 s[36:37], 0x30000
	v_lshl_add_u64 v[178:179], v[216:217], 0, s[36:37]
	v_add_u32_e32 v215, 0x60000, v214
	v_lshlrev_b32_e32 v216, 2, v215
	v_and_b32_e32 v228, 0xffc, v216
	v_bfe_u32 v216, v216, 8, 4
	v_ashrrev_i32_e32 v217, 14, v215
	s_mov_b32 s10, 0x1ffffff0
	v_and_or_b32 v216, v217, s10, v216
	v_lshlrev_b32_e32 v216, 3, v216
	v_ashrrev_i32_e32 v217, 31, v216
	v_lshlrev_b64 v[216:217], 18, v[216:217]
	v_lshl_add_u64 v[216:217], s[2:3], 0, v[216:217]
	v_and_b32_e32 v228, 0x3fc00, v215
	v_lshl_add_u64 v[216:217], v[216:217], 0, v[228:229]
	v_lshlrev_b32_e32 v228, 4, v215
	v_and_b32_e32 v228, 0x3f0, v228
	v_lshl_add_u64 v[224:225], v[216:217], 0, v[228:229]
	v_ashrrev_i32_e32 v216, 10, v215
	v_ashrrev_i32_e32 v217, 31, v216
	v_lshlrev_b64 v[216:217], 14, v[216:217]
	v_lshlrev_b32_e32 v228, 2, v215
	v_and_b32_e32 v228, 0xffc, v228
	v_lshlrev_b32_e32 v228, 2, v228
	v_lshl_add_u64 v[226:227], s[0:1], 0, v[216:217]
	v_lshl_add_u64 v[236:237], v[226:227], 0, v[228:229]
	v_lshl_add_u64 v[226:227], s[6:7], 0, v[216:217]
	v_lshl_add_u64 v[244:245], v[226:227], 0, v[228:229]
	v_ashrrev_i32_e32 v216, 15, v215
	v_mul_i32_i24_e32 v216, 0x3000, v216
	v_ashrrev_i32_e32 v217, 31, v216
	v_lshl_add_u64 v[216:217], v[216:217], 2, s[4:5]
	v_lshl_add_u64 v[216:217], v[216:217], 0, v[228:229]
	s_mov_b64 s[36:37], 0x30000
	v_lshl_add_u64 v[180:181], v[216:217], 0, s[36:37]
	s_waitcnt lgkmcnt(0)
	s_barrier
; __global__ void __launch_bounds__(NWAVES * 64, 2) mk_fwd(Args args) {
;     ...
;                     for (int q = 0; q < 4; ++q) { const int idx = q * (G * 512) + bx * 512 + tid, r = idx >> 10, c = (idx & 1023) * 4;
;                         const float* pp = part + ((size_t)(((r >> 8) * 16 + (c >> 8)) * 8) * 65536 + (size_t)(r & 255) * 256 + (c & 255));
;                         f32x4 a = *(const f32x4*)pp;
; #pragma unroll
;                         for (int k2 = 1; k2 < 8; ++k2) a += *(const f32x4*)(pp + (size_t)k2 * 65536);
;                         ra[q] = a; rx[q] = *(const f32x4*)(xs + (size_t)r * DM + c); rg[q] = *(const f32x4*)(gate + (size_t)(4 + (r >> 5)) * (3 * DM) + c); }
	global_load_dwordx4 v[4:7], v[218:219], off
	s_mov_b64 s[36:37], 0x40000
	v_lshl_add_u64 v[216:217], v[218:219], 0, s[36:37]
	global_load_dwordx4 v[8:11], v[216:217], off
	s_mov_b64 s[36:37], 0x80000
	v_lshl_add_u64 v[216:217], v[218:219], 0, s[36:37]
	global_load_dwordx4 v[12:15], v[216:217], off
	s_mov_b64 s[36:37], 0xc0000
	v_lshl_add_u64 v[216:217], v[218:219], 0, s[36:37]
	global_load_dwordx4 v[16:19], v[216:217], off
	s_mov_b64 s[36:37], 0x100000
	v_lshl_add_u64 v[216:217], v[218:219], 0, s[36:37]
	global_load_dwordx4 v[20:23], v[216:217], off
	s_mov_b64 s[36:37], 0x140000
	v_lshl_add_u64 v[216:217], v[218:219], 0, s[36:37]
	global_load_dwordx4 v[24:27], v[216:217], off
	s_mov_b64 s[36:37], 0x180000
	v_lshl_add_u64 v[216:217], v[218:219], 0, s[36:37]
	global_load_dwordx4 v[28:31], v[216:217], off
	s_mov_b64 s[36:37], 0x1c0000
	v_lshl_add_u64 v[216:217], v[218:219], 0, s[36:37]
	global_load_dwordx4 v[32:35], v[216:217], off
	global_load_dwordx4 v[36:39], v[238:239], off
	global_load_dwordx4 v[40:43], v[174:175], off
	global_load_dwordx4 v[44:47], v[220:221], off
	s_mov_b64 s[36:37], 0x40000
	v_lshl_add_u64 v[216:217], v[220:221], 0, s[36:37]
	global_load_dwordx4 v[48:51], v[216:217], off
	s_mov_b64 s[36:37], 0x80000
	v_lshl_add_u64 v[216:217], v[220:221], 0, s[36:37]
	global_load_dwordx4 v[52:55], v[216:217], off
	s_mov_b64 s[36:37], 0xc0000
	v_lshl_add_u64 v[216:217], v[220:221], 0, s[36:37]
	global_load_dwordx4 v[56:59], v[216:217], off
	s_mov_b64 s[36:37], 0x100000
	v_lshl_add_u64 v[216:217], v[220:221], 0, s[36:37]
	global_load_dwordx4 v[60:63], v[216:217], off
	s_mov_b64 s[36:37], 0x140000
	v_lshl_add_u64 v[216:217], v[220:221], 0, s[36:37]
	global_load_dwordx4 v[64:67], v[216:217], off
	s_mov_b64 s[36:37], 0x180000
	v_lshl_add_u64 v[216:217], v[220:221], 0, s[36:37]
	global_load_dwordx4 v[68:71], v[216:217], off
	s_mov_b64 s[36:37], 0x1c0000
	v_lshl_add_u64 v[216:217], v[220:221], 0, s[36:37]
	global_load_dwordx4 v[72:75], v[216:217], off
	global_load_dwordx4 v[76:79], v[240:241], off
	global_load_dwordx4 v[80:83], v[176:177], off
	global_load_dwordx4 v[84:87], v[222:223], off
	s_mov_b64 s[36:37], 0x40000
	v_lshl_add_u64 v[216:217], v[222:223], 0, s[36:37]
	global_load_dwordx4 v[88:91], v[216:217], off
	s_mov_b64 s[36:37], 0x80000
	v_lshl_add_u64 v[216:217], v[222:223], 0, s[36:37]
	global_load_dwordx4 v[92:95], v[216:217], off
	s_mov_b64 s[36:37], 0xc0000
	v_lshl_add_u64 v[216:217], v[222:223], 0, s[36:37]
	global_load_dwordx4 v[96:99], v[216:217], off
	s_mov_b64 s[36:37], 0x100000
	v_lshl_add_u64 v[216:217], v[222:223], 0, s[36:37]
	global_load_dwordx4 v[100:103], v[216:217], off
	s_mov_b64 s[36:37], 0x140000
	v_lshl_add_u64 v[216:217], v[222:223], 0, s[36:37]
	global_load_dwordx4 v[104:107], v[216:217], off
	s_mov_b64 s[36:37], 0x180000
	v_lshl_add_u64 v[216:217], v[222:223], 0, s[36:37]
	global_load_dwordx4 v[108:111], v[216:217], off
	s_mov_b64 s[36:37], 0x1c0000
	v_lshl_add_u64 v[216:217], v[222:223], 0, s[36:37]
	global_load_dwordx4 v[112:115], v[216:217], off
	global_load_dwordx4 v[116:119], v[242:243], off
	global_load_dwordx4 v[120:123], v[178:179], off
	global_load_dwordx4 v[124:127], v[224:225], off
	s_mov_b64 s[36:37], 0x40000
	v_lshl_add_u64 v[216:217], v[224:225], 0, s[36:37]
	global_load_dwordx4 v[128:131], v[216:217], off
	s_mov_b64 s[36:37], 0x80000
	v_lshl_add_u64 v[216:217], v[224:225], 0, s[36:37]
	global_load_dwordx4 v[132:135], v[216:217], off
	s_mov_b64 s[36:37], 0xc0000
	v_lshl_add_u64 v[216:217], v[224:225], 0, s[36:37]
	global_load_dwordx4 v[136:139], v[216:217], off
	s_mov_b64 s[36:37], 0x100000
	v_lshl_add_u64 v[216:217], v[224:225], 0, s[36:37]
	global_load_dwordx4 v[140:143], v[216:217], off
	s_mov_b64 s[36:37], 0x140000
	v_lshl_add_u64 v[216:217], v[224:225], 0, s[36:37]
	global_load_dwordx4 v[144:147], v[216:217], off
	s_mov_b64 s[36:37], 0x180000
	v_lshl_add_u64 v[216:217], v[224:225], 0, s[36:37]
	global_load_dwordx4 v[148:151], v[216:217], off
	s_mov_b64 s[36:37], 0x1c0000
	v_lshl_add_u64 v[216:217], v[224:225], 0, s[36:37]
	global_load_dwordx4 v[152:155], v[216:217], off
	global_load_dwordx4 v[156:159], v[244:245], off
	global_load_dwordx4 v[210:213], v[180:181], off
	s_waitcnt vmcnt(0)
; __global__ void __launch_bounds__(NWAVES * 64, 2) mk_fwd(Args args) {
;     ...
;                         f32x4 a = *(const f32x4*)pp;
; #pragma unroll
;                         for (int k2 = 1; k2 < 8; ++k2) a += *(const f32x4*)(pp + (size_t)k2 * 65536);
;                         ra[q] = a; rx[q] = *(const f32x4*)(xs + (size_t)r * DM + c); rg[q] = *(const f32x4*)(gate + (size_t)(4 + (r >> 5)) * (3 * DM) + c); }
; #pragma unroll
;                     for (int q = 0; q < 4; ++q) { const int idx = q * (G * 512) + bx * 512 + tid, r = idx >> 10, c = (idx & 1023) * 4;
;                         *(f32x4*)(out + O_YS + (size_t)r * DM + c) = rx[q] + rg[q] * ra[q]; }
	v_pk_add_f32 v[8:9], v[4:5], v[8:9]
	v_pk_add_f32 v[10:11], v[6:7], v[10:11]
	v_pk_add_f32 v[8:9], v[8:9], v[12:13]
	v_pk_add_f32 v[10:11], v[10:11], v[14:15]
	v_pk_add_f32 v[8:9], v[8:9], v[16:17]
	v_pk_add_f32 v[10:11], v[10:11], v[18:19]
	v_pk_add_f32 v[8:9], v[8:9], v[20:21]
	v_pk_add_f32 v[10:11], v[10:11], v[22:23]
	v_pk_add_f32 v[8:9], v[8:9], v[24:25]
	v_pk_add_f32 v[10:11], v[10:11], v[26:27]
	v_pk_add_f32 v[8:9], v[8:9], v[28:29]
	v_pk_add_f32 v[10:11], v[10:11], v[30:31]
	v_pk_add_f32 v[8:9], v[8:9], v[32:33]
	v_pk_add_f32 v[10:11], v[10:11], v[34:35]
	v_pk_fma_f32 v[4:5], v[40:41], v[8:9], v[36:37]
	v_pk_fma_f32 v[6:7], v[42:43], v[10:11], v[38:39]
	global_store_dwordx4 v[230:231], v[4:7], off
	v_pk_add_f32 v[48:49], v[44:45], v[48:49]
	v_pk_add_f32 v[50:51], v[46:47], v[50:51]
	v_pk_add_f32 v[48:49], v[48:49], v[52:53]
	v_pk_add_f32 v[50:51], v[50:51], v[54:55]
	v_pk_add_f32 v[48:49], v[48:49], v[56:57]
	v_pk_add_f32 v[50:51], v[50:51], v[58:59]
	v_pk_add_f32 v[48:49], v[48:49], v[60:61]
	v_pk_add_f32 v[50:51], v[50:51], v[62:63]
	v_pk_add_f32 v[48:49], v[48:49], v[64:65]
	v_pk_add_f32 v[50:51], v[50:51], v[66:67]
	v_pk_add_f32 v[48:49], v[48:49], v[68:69]
	v_pk_add_f32 v[50:51], v[50:51], v[70:71]
	v_pk_add_f32 v[48:49], v[48:49], v[72:73]
	v_pk_add_f32 v[50:51], v[50:51], v[74:75]
	v_pk_fma_f32 v[44:45], v[80:81], v[48:49], v[76:77]
	v_pk_fma_f32 v[46:47], v[82:83], v[50:51], v[78:79]
	global_store_dwordx4 v[232:233], v[44:47], off
	v_pk_add_f32 v[88:89], v[84:85], v[88:89]
	v_pk_add_f32 v[90:91], v[86:87], v[90:91]
	v_pk_add_f32 v[88:89], v[88:89], v[92:93]
	v_pk_add_f32 v[90:91], v[90:91], v[94:95]
	v_pk_add_f32 v[88:89], v[88:89], v[96:97]
	v_pk_add_f32 v[90:91], v[90:91], v[98:99]
	v_pk_add_f32 v[88:89], v[88:89], v[100:101]
	v_pk_add_f32 v[90:91], v[90:91], v[102:103]
	v_pk_add_f32 v[88:89], v[88:89], v[104:105]
	v_pk_add_f32 v[90:91], v[90:91], v[106:107]
	v_pk_add_f32 v[88:89], v[88:89], v[108:109]
	v_pk_add_f32 v[90:91], v[90:91], v[110:111]
	v_pk_add_f32 v[88:89], v[88:89], v[112:113]
	v_pk_add_f32 v[90:91], v[90:91], v[114:115]
	v_pk_fma_f32 v[84:85], v[120:121], v[88:89], v[116:117]
	v_pk_fma_f32 v[86:87], v[122:123], v[90:91], v[118:119]
	global_store_dwordx4 v[234:235], v[84:87], off
	v_pk_add_f32 v[128:129], v[124:125], v[128:129]
	v_pk_add_f32 v[130:131], v[126:127], v[130:131]
	v_pk_add_f32 v[128:129], v[128:129], v[132:133]
	v_pk_add_f32 v[130:131], v[130:131], v[134:135]
	v_pk_add_f32 v[128:129], v[128:129], v[136:137]
	v_pk_add_f32 v[130:131], v[130:131], v[138:139]
	v_pk_add_f32 v[128:129], v[128:129], v[140:141]
	v_pk_add_f32 v[130:131], v[130:131], v[142:143]
	v_pk_add_f32 v[128:129], v[128:129], v[144:145]
	v_pk_add_f32 v[130:131], v[130:131], v[146:147]
	v_pk_add_f32 v[128:129], v[128:129], v[148:149]
	v_pk_add_f32 v[130:131], v[130:131], v[150:151]
	v_pk_add_f32 v[128:129], v[128:129], v[152:153]
	v_pk_add_f32 v[130:131], v[130:131], v[154:155]
	v_pk_fma_f32 v[124:125], v[210:211], v[128:129], v[156:157]
	v_pk_fma_f32 v[126:127], v[212:213], v[130:131], v[158:159]
	global_store_dwordx4 v[236:237], v[124:127], off
